# batched the four serialized norm-weight loads of the projection QK-norm epilogue, the 16 serialized residual loads of the output-projection epilogue and its four SSQ prologue loads
# speedup vs baseline: 1.0335x; 1.0061x over previous
; DI float bperm(float x, int srclane) { return __int_as_float(__builtin_amdgcn_ds_bpermute(srclane << 2, __float_as_int(x))); }
; DI float sx16(float x) { return swzf<0x401F>(x); }
; DI void phase_inproj(int wv, const Params& p, int layer, char* smc) {
;     ...
;     if (isq || isk) {
;       const float* nw = isq ? PW(p, 27) + layer * 64 : PW(p, 28) + layer * 64;
;       const float sc = isq ? 0.125f : 1.f;
;       float nwr[4][4];
; #pragma unroll
;       for (int n = 0; n < 4; ++n)
; #pragma unroll
;         for (int jj = 0; jj < 4; ++jj) nwr[n][jj] = nw[n * 16 + 4 * fq + jj] * sc;
; #pragma unroll
;       for (int i = 0; i < 4; ++i) {
;         float ss = 0.f;
; #pragma unroll
;         for (int n = 0; n < 4; ++n)
; #pragma unroll
;           for (int jj = 0; jj < 4; ++jj) ss += acc[i][n][jj] * acc[i][n][jj];
;         ss += sx16(ss);
;         ss += bperm(ss, lane ^ 32);
;         const float rs = rsqrtf(ss * (1.f / 64.f) + 1e-6f);
.LBB0_162:
	s_lshl_b32 s7, s6, 7
	s_add_i32 s0, s7, 0xffffe980
	s_cmpk_lt_u32 s0, 0x200
	s_cselect_b64 s[0:1], -1, 0
	s_add_i32 s15, s7, 0xffffe700
	s_cmpk_lt_u32 s15, 0x200
	s_cselect_b64 s[16:17], -1, 0
	s_or_b64 s[16:17], s[0:1], s[16:17]
	s_andn2_b64 vcc, exec, s[16:17]
	s_cbranch_vccnz .LBB0_164
	s_waitcnt vmcnt(3)
	v_mov_b32_e32 v84, v7
	v_mov_b32_e32 v85, v3
	v_mov_b32_e32 v82, v6
	v_mov_b32_e32 v83, v2
	v_pk_mul_f32 v[84:85], v[84:85], v[84:85]
	v_pk_mul_f32 v[72:73], v[14:15], v[14:15]
	v_pk_fma_f32 v[82:83], v[82:83], v[82:83], v[84:85]
	v_mov_b32_e32 v84, v8
	v_mov_b32_e32 v85, v4
	v_pk_fma_f32 v[82:83], v[84:85], v[84:85], v[82:83]
	v_mov_b32_e32 v84, v9
	v_mov_b32_e32 v85, v5
	v_pk_fma_f32 v[82:83], v[84:85], v[84:85], v[82:83]
	v_mov_b32_e32 v84, v22
	v_mov_b32_e32 v85, v18
	v_pk_fma_f32 v[82:83], v[84:85], v[84:85], v[82:83]
	v_mov_b32_e32 v84, v23
	v_mov_b32_e32 v85, v19
	v_pk_fma_f32 v[82:83], v[84:85], v[84:85], v[82:83]
	v_mov_b32_e32 v84, v24
	v_mov_b32_e32 v85, v20
	v_pk_mul_f32 v[80:81], v[26:27], v[26:27]
	v_pk_fma_f32 v[82:83], v[84:85], v[84:85], v[82:83]
	v_mov_b32_e32 v84, v25
	v_mov_b32_e32 v85, v21
	v_pk_fma_f32 v[82:83], v[84:85], v[84:85], v[82:83]
	v_mov_b32_e32 v84, v80
	v_mov_b32_e32 v85, v72
	v_pk_mul_f32 v[68:69], v[16:17], v[16:17]
	v_pk_mul_f32 v[78:79], v[28:29], v[28:29]
	v_pk_add_f32 v[82:83], v[84:85], v[82:83]
	v_mov_b32_e32 v72, v81
	v_pk_add_f32 v[72:73], v[72:73], v[82:83]
	v_mov_b32_e32 v80, v78
	v_mov_b32_e32 v81, v68
	v_pk_mul_f32 v[76:77], v[10:11], v[10:11]
	s_waitcnt vmcnt(2)
	v_pk_mul_f32 v[86:87], v[30:31], v[30:31]
	v_pk_add_f32 v[72:73], v[80:81], v[72:73]
	v_mov_b32_e32 v68, v79
	v_pk_add_f32 v[68:69], v[68:69], v[72:73]
	v_mov_b32_e32 v72, v86
	v_mov_b32_e32 v73, v76
	v_pk_mul_f32 v[74:75], v[12:13], v[12:13]
	v_pk_mul_f32 v[84:85], v[32:33], v[32:33]
	v_pk_add_f32 v[68:69], v[72:73], v[68:69]
	v_mov_b32_e32 v76, v87
	v_pk_add_f32 v[68:69], v[76:77], v[68:69]
	v_mov_b32_e32 v72, v84
	v_mov_b32_e32 v73, v74
	v_pk_add_f32 v[68:69], v[72:73], v[68:69]
	v_mov_b32_e32 v74, v85
	v_pk_add_f32 v[68:69], v[74:75], v[68:69]
	ds_swizzle_b32 v73, v69 offset:swizzle(SWAP,16)
	ds_swizzle_b32 v72, v68 offset:swizzle(SWAP,16)
	v_mov_b32_e32 v66, 0x3e000000
	s_and_b64 s[16:17], s[0:1], exec
	v_cndmask_b32_e64 v70, 1.0, v66, s[0:1]
	s_mov_b32 s0, 0x358637bd
	s_waitcnt lgkmcnt(0)
	v_pk_add_f32 v[68:69], v[68:69], v[72:73]
	ds_bpermute_b32 v73, v131, v69
	ds_bpermute_b32 v72, v131, v68
	v_mov_b64_e32 v[76:77], s[0:1]
	s_mov_b32 s16, 0x3c800000
	s_waitcnt vmcnt(1)
	v_mov_b32_e32 v90, v51
	v_mov_b32_e32 v91, v35
	s_waitcnt lgkmcnt(0)
	v_pk_add_f32 v[68:69], v[68:69], v[72:73]
	v_mov_b32_e32 v88, v50
	v_pk_fma_f32 v[68:69], v[68:69], s[16:17], v[76:77] op_sel_hi:[1,0,0]
	v_mov_b32_e32 v89, v34
	v_mul_f32_e32 v71, 0x4b800000, v69
	v_cmp_gt_f32_e64 s[0:1], s72, v69
	v_pk_mul_f32 v[90:91], v[90:91], v[90:91]
	v_cmp_gt_f32_e32 vcc, s72, v68
	v_cndmask_b32_e64 v69, v69, v71, s[0:1]
	v_rsq_f32_e32 v69, v69
	v_pk_fma_f32 v[88:89], v[88:89], v[88:89], v[90:91]
	v_mov_b32_e32 v90, v52
	v_mov_b32_e32 v91, v36
	v_mul_f32_e32 v71, 0x45800000, v69
	v_cndmask_b32_e64 v72, v69, v71, s[0:1]
	v_mul_f32_e32 v69, 0x4b800000, v68
	v_cndmask_b32_e32 v68, v68, v69, vcc
	v_pk_fma_f32 v[88:89], v[90:91], v[90:91], v[88:89]
	v_mov_b32_e32 v90, v53
	v_mov_b32_e32 v91, v37
	v_rsq_f32_e32 v68, v68
	v_pk_fma_f32 v[88:89], v[90:91], v[90:91], v[88:89]
	v_mov_b32_e32 v90, v54
	v_mov_b32_e32 v91, v38
	v_pk_fma_f32 v[88:89], v[90:91], v[90:91], v[88:89]
	v_mov_b32_e32 v90, v55
	v_mov_b32_e32 v91, v39
	v_pk_fma_f32 v[88:89], v[90:91], v[90:91], v[88:89]
	v_mov_b32_e32 v90, v56
	v_mov_b32_e32 v91, v40
	v_pk_mul_f32 v[78:79], v[42:43], v[42:43]
	v_pk_mul_f32 v[86:87], v[58:59], v[58:59]
	v_pk_fma_f32 v[88:89], v[90:91], v[90:91], v[88:89]
	v_mov_b32_e32 v90, v57
	v_mov_b32_e32 v91, v41
	v_mul_f32_e32 v69, 0x45800000, v68
	v_pk_fma_f32 v[88:89], v[90:91], v[90:91], v[88:89]
	v_mov_b32_e32 v90, v86
	v_mov_b32_e32 v91, v78
	v_cndmask_b32_e32 v74, v68, v69, vcc
	v_pk_mul_f32 v[68:69], v[44:45], v[44:45]
	v_pk_mul_f32 v[84:85], v[60:61], v[60:61]
	v_pk_add_f32 v[88:89], v[90:91], v[88:89]
	v_mov_b32_e32 v78, v87
	v_pk_add_f32 v[78:79], v[78:79], v[88:89]
	v_mov_b32_e32 v86, v84
	v_mov_b32_e32 v87, v68
	v_pk_mul_f32 v[82:83], v[46:47], v[46:47]
	v_pk_mul_f32 v[92:93], v[62:63], v[62:63]
	v_pk_add_f32 v[78:79], v[86:87], v[78:79]
	v_mov_b32_e32 v68, v85
	v_pk_add_f32 v[68:69], v[68:69], v[78:79]
	v_mov_b32_e32 v78, v92
	v_mov_b32_e32 v79, v82
	s_mov_b32 s15, 0x3cda0800
	v_pk_mul_f32 v[80:81], v[48:49], v[48:49]
	v_pk_mul_f32 v[90:91], v[64:65], v[64:65]
	v_pk_add_f32 v[68:69], v[78:79], v[68:69]
	v_mov_b32_e32 v82, v93
	s_cselect_b32 s54, s15, 0x3cda0a00
	v_pk_add_f32 v[68:69], v[82:83], v[68:69]
	v_mov_b32_e32 v78, v90
	v_mov_b32_e32 v79, v80
	v_lshl_add_u64 v[66:67], v[138:139], 0, s[54:55]
	v_pk_add_f32 v[68:69], v[78:79], v[68:69]
	v_mov_b32_e32 v80, v91
	v_pk_add_f32 v[68:69], v[80:81], v[68:69]
	global_load_dwordx4 v[80:83], v[66:67], off
	global_load_dwordx4 v[184:187], v[66:67], off offset:64
	global_load_dwordx4 v[188:191], v[66:67], off offset:128
	global_load_dwordx4 v[192:195], v[66:67], off offset:192
	ds_swizzle_b32 v79, v69 offset:swizzle(SWAP,16)
	ds_swizzle_b32 v78, v68 offset:swizzle(SWAP,16)
	s_waitcnt lgkmcnt(0)
; DI float bperm(float x, int srclane) { return __int_as_float(__builtin_amdgcn_ds_bpermute(srclane << 2, __float_as_int(x))); }
; DI float sx16(float x) { return swzf<0x401F>(x); }
; DI void phase_inproj(int wv, const Params& p, int layer, char* smc) {
;     ...
;       for (int i = 0; i < 4; ++i) {
;         float ss = 0.f;
; #pragma unroll
;         for (int n = 0; n < 4; ++n)
; #pragma unroll
;           for (int jj = 0; jj < 4; ++jj) ss += acc[i][n][jj] * acc[i][n][jj];
;         ss += sx16(ss);
;         ss += bperm(ss, lane ^ 32);
;         const float rs = rsqrtf(ss * (1.f / 64.f) + 1e-6f);
; #pragma unroll
;         for (int n = 0; n < 4; ++n)
; #pragma unroll
;           for (int jj = 0; jj < 4; ++jj) acc[i][n][jj] *= rs * nwr[n][jj];
;       }
	v_pk_add_f32 v[68:69], v[68:69], v[78:79]
	ds_bpermute_b32 v79, v131, v69
	ds_bpermute_b32 v78, v131, v68
	s_waitcnt lgkmcnt(0)
	v_pk_add_f32 v[68:69], v[68:69], v[78:79]
	s_nop 0
	v_pk_fma_f32 v[68:69], v[68:69], s[16:17], v[76:77] op_sel_hi:[1,0,0]
	s_nop 0
	v_mul_f32_e32 v71, 0x4b800000, v69
	v_cmp_gt_f32_e64 s[0:1], s72, v69
	v_cmp_gt_f32_e32 vcc, s72, v68
	s_nop 0
	v_cndmask_b32_e64 v69, v69, v71, s[0:1]
	v_rsq_f32_e32 v69, v69
	s_nop 0
	v_mul_f32_e32 v71, 0x45800000, v69
	v_cndmask_b32_e64 v78, v69, v71, s[0:1]
	v_mul_f32_e32 v69, 0x4b800000, v68
	v_cndmask_b32_e32 v68, v68, v69, vcc
	v_rsq_f32_e32 v68, v68
	s_nop 0
	v_mul_f32_e32 v69, 0x45800000, v68
	v_cndmask_b32_e32 v76, v68, v69, vcc
	s_waitcnt vmcnt(0)
	v_pk_mul_f32 v[68:69], v[70:71], v[80:81] op_sel_hi:[0,1]
	v_pk_mul_f32 v[80:81], v[70:71], v[82:83] op_sel_hi:[0,1]
	v_pk_mul_f32 v[82:83], v[68:69], v[72:73] op_sel_hi:[1,0]
	v_pk_mul_f32 v[84:85], v[80:81], v[72:73] op_sel_hi:[1,0]
	v_pk_mul_f32 v[2:3], v[2:3], v[82:83]
	v_pk_mul_f32 v[4:5], v[4:5], v[84:85]
	v_pk_mul_f32 v[82:83], v[68:69], v[74:75] op_sel_hi:[1,0]
	v_pk_mul_f32 v[84:85], v[80:81], v[74:75] op_sel_hi:[1,0]
	v_pk_mul_f32 v[6:7], v[6:7], v[82:83]
	v_pk_mul_f32 v[8:9], v[8:9], v[84:85]
	v_pk_mul_f32 v[82:83], v[68:69], v[78:79] op_sel_hi:[1,0]
	v_pk_mul_f32 v[84:85], v[80:81], v[78:79] op_sel_hi:[1,0]
	v_pk_mul_f32 v[80:81], v[80:81], v[76:77] op_sel_hi:[1,0]
	v_pk_mul_f32 v[34:35], v[34:35], v[82:83]
	v_pk_mul_f32 v[52:53], v[52:53], v[80:81]
	v_mov_b64_e32 v[80:81], v[184:185]
	v_mov_b64_e32 v[82:83], v[186:187]
	v_pk_mul_f32 v[68:69], v[68:69], v[76:77] op_sel_hi:[1,0]
	v_pk_mul_f32 v[36:37], v[36:37], v[84:85]
	v_pk_mul_f32 v[50:51], v[50:51], v[68:69]
	s_waitcnt vmcnt(0)
	v_pk_mul_f32 v[68:69], v[70:71], v[80:81] op_sel_hi:[0,1]
	v_pk_mul_f32 v[80:81], v[70:71], v[82:83] op_sel_hi:[0,1]
	v_pk_mul_f32 v[82:83], v[68:69], v[72:73] op_sel_hi:[1,0]
	v_pk_mul_f32 v[84:85], v[80:81], v[72:73] op_sel_hi:[1,0]
	v_pk_mul_f32 v[18:19], v[18:19], v[82:83]
	v_pk_mul_f32 v[20:21], v[20:21], v[84:85]
	v_pk_mul_f32 v[82:83], v[68:69], v[74:75] op_sel_hi:[1,0]
	v_pk_mul_f32 v[84:85], v[80:81], v[74:75] op_sel_hi:[1,0]
	v_pk_mul_f32 v[22:23], v[22:23], v[82:83]
	v_pk_mul_f32 v[24:25], v[24:25], v[84:85]
	v_pk_mul_f32 v[82:83], v[68:69], v[78:79] op_sel_hi:[1,0]
	v_pk_mul_f32 v[84:85], v[80:81], v[78:79] op_sel_hi:[1,0]
	v_pk_mul_f32 v[80:81], v[80:81], v[76:77] op_sel_hi:[1,0]
	v_pk_mul_f32 v[38:39], v[38:39], v[82:83]
	v_pk_mul_f32 v[56:57], v[56:57], v[80:81]
	v_mov_b64_e32 v[80:81], v[188:189]
	v_mov_b64_e32 v[82:83], v[190:191]
	v_pk_mul_f32 v[68:69], v[68:69], v[76:77] op_sel_hi:[1,0]
	v_pk_mul_f32 v[40:41], v[40:41], v[84:85]
	v_pk_mul_f32 v[54:55], v[54:55], v[68:69]
	s_waitcnt vmcnt(0)
	v_pk_mul_f32 v[68:69], v[70:71], v[80:81] op_sel_hi:[0,1]
	v_pk_mul_f32 v[80:81], v[70:71], v[82:83] op_sel_hi:[0,1]
	v_pk_mul_f32 v[82:83], v[68:69], v[72:73] op_sel_hi:[1,0]
	v_pk_mul_f32 v[84:85], v[80:81], v[72:73] op_sel_hi:[1,0]
	v_pk_mul_f32 v[14:15], v[14:15], v[82:83]
	v_pk_mul_f32 v[82:83], v[68:69], v[74:75] op_sel_hi:[1,0]
	v_pk_mul_f32 v[16:17], v[16:17], v[84:85]
	v_pk_mul_f32 v[26:27], v[26:27], v[82:83]
	v_pk_mul_f32 v[82:83], v[68:69], v[78:79] op_sel_hi:[1,0]
	v_pk_mul_f32 v[68:69], v[68:69], v[76:77] op_sel_hi:[1,0]
	v_pk_mul_f32 v[84:85], v[80:81], v[74:75] op_sel_hi:[1,0]
	v_pk_mul_f32 v[58:59], v[58:59], v[68:69]
	v_mov_b64_e32 v[68:69], v[194:195]
	v_mov_b64_e32 v[66:67], v[192:193]
	v_pk_mul_f32 v[28:29], v[28:29], v[84:85]
	v_pk_mul_f32 v[84:85], v[80:81], v[78:79] op_sel_hi:[1,0]
	v_pk_mul_f32 v[80:81], v[80:81], v[76:77] op_sel_hi:[1,0]
	v_pk_mul_f32 v[44:45], v[44:45], v[84:85]
	v_pk_mul_f32 v[42:43], v[42:43], v[82:83]
	v_pk_mul_f32 v[60:61], v[60:61], v[80:81]
	s_waitcnt vmcnt(0)
	v_pk_mul_f32 v[66:67], v[70:71], v[66:67] op_sel_hi:[0,1]
	v_pk_mul_f32 v[68:69], v[70:71], v[68:69] op_sel_hi:[0,1]
	v_pk_mul_f32 v[70:71], v[66:67], v[72:73] op_sel_hi:[1,0]
	v_pk_mul_f32 v[72:73], v[68:69], v[72:73] op_sel_hi:[1,0]
	v_pk_mul_f32 v[10:11], v[10:11], v[70:71]
	v_pk_mul_f32 v[12:13], v[12:13], v[72:73]
	v_pk_mul_f32 v[70:71], v[66:67], v[74:75] op_sel_hi:[1,0]
	v_pk_mul_f32 v[72:73], v[68:69], v[74:75] op_sel_hi:[1,0]
	v_pk_mul_f32 v[30:31], v[30:31], v[70:71]
	v_pk_mul_f32 v[32:33], v[32:33], v[72:73]
	v_pk_mul_f32 v[70:71], v[66:67], v[78:79] op_sel_hi:[1,0]
	v_pk_mul_f32 v[72:73], v[68:69], v[78:79] op_sel_hi:[1,0]
	v_pk_mul_f32 v[66:67], v[66:67], v[76:77] op_sel_hi:[1,0]
	v_pk_mul_f32 v[68:69], v[68:69], v[76:77] op_sel_hi:[1,0]
	v_pk_mul_f32 v[48:49], v[48:49], v[72:73]
	v_pk_mul_f32 v[46:47], v[46:47], v[70:71]
	v_pk_mul_f32 v[64:65], v[64:65], v[68:69]
	v_pk_mul_f32 v[62:63], v[62:63], v[66:67]

; DI void gemm_mainloop(int wv, const u16* __restrict__ A, long lda, long a_kstep, const u16* __restrict__ Bt, long ldb, int K,
;                       char* smc, f32x4 (&acc)[4][4], const bool seg = false, const float* sc0 = nullptr, const float* sc1 = nullptr) {
;     ...
;   const int lr = tid >> 3, lc = tid & 7;
;   const u16* ag = A + (long)lr * lda + lc * 8;
;   const u16* bg = Bt + (long)lr * ldb + lc * 8;
;   const int nk = K / 64;
; #pragma unroll
;   for (int i = 0; i < 4; ++i) {
;     ra[i] = *(const u32x4*)(ag + (long)(32 * i) * lda);
;     rb[i] = *(const u32x4*)(bg + (long)(32 * i) * ldb);
;   }
; #pragma unroll
;   for (int i = 0; i < 4; ++i) {
;     ra2[i] = *(const u32x4*)(ag + (long)(32 * i) * lda + a_kstep);
;     rb2[i] = *(const u32x4*)(bg + (long)(32 * i) * ldb + 64);
;   }
; DI void phase_outproj(int wv, const Params& p, int layer, char* smc) {
;     ...
;   for (int tl = slot; tl < nmt * NTN; tl += nslots) {
;     const int tn = tl % NTN, tm = (tl / NTN) * 8 + xcd;
;     f32x4 acc[4][4];
;     float sc0[4], sc1[4];
;     {
;       const float* SSQ = (const float*)(p.ws + wsSSQ);
; #pragma unroll
;       for (int i = 0; i < 4; ++i) {
;         const long row = (long)tm * 128 + wm * 64 + i * 16 + fr;
;         sc0[i] = rsqrtf(SSQ[row * 2 + 0] * (1.f / 384.f) + 1e-5f);
;         sc1[i] = rsqrtf(SSQ[row * 2 + 1] * (1.f / 384.f) + 1e-5f);
;       }
;     }
.Lop_next:
	s_add_i32 s12, s12, s11
	v_readlane_b32 s0, v255, 2
	s_cmp_lt_u32 s12, s0
	s_cbranch_scc0 .LBB0_929
.LBB0_855:
	s_and_b32 s0, s12, 0x7ffffff8
	s_or_b32 s54, s0, s86
	s_lshl_b64 s[0:1], s[54:55], 7
	v_lshl_add_u64 v[140:141], s[0:1], 0, v[132:133]
	v_lshl_add_u64 v[2:3], v[140:141], 3, s[66:67]
	global_load_dwordx2 v[2:3], v[2:3], off
	s_mov_b32 s0, 0x3727c5ac
	v_mov_b64_e32 v[4:5], s[0:1]
	s_mov_b32 s4, 0x3b2aaaab
	v_or_b32_e32 v138, 16, v140
	v_mov_b32_e32 v139, v141
	v_or_b32_e32 v136, 32, v140
	v_mov_b32_e32 v137, v141
	v_or_b32_e32 v134, 48, v140
	v_mov_b32_e32 v135, v141
	v_mov_b32_e32 v71, v209
	s_and_b32 s13, s12, 7
	v_mov_b32_e32 v7, v0
	s_mov_b32 s14, 0
	v_lshl_add_u64 v[184:185], v[138:139], 3, s[66:67]
	global_load_dwordx2 v[184:185], v[184:185], off
	v_lshl_add_u64 v[186:187], v[136:137], 3, s[66:67]
	global_load_dwordx2 v[186:187], v[186:187], off
	v_lshl_add_u64 v[188:189], v[134:135], 3, s[66:67]
	global_load_dwordx2 v[188:189], v[188:189], off
	s_waitcnt vmcnt(0)
	v_pk_fma_f32 v[2:3], v[2:3], s[4:5], v[4:5] op_sel_hi:[1,0,0]
	s_nop 0
	v_mul_f32_e32 v1, 0x4b800000, v2
	v_cmp_gt_f32_e64 s[0:1], s72, v2
	v_cmp_gt_f32_e32 vcc, s72, v3
	s_nop 0
	v_cndmask_b32_e64 v1, v2, v1, s[0:1]
	v_rsq_f32_e32 v1, v1
	s_nop 0
	v_mul_f32_e32 v2, 0x45800000, v1
	v_cndmask_b32_e64 v68, v1, v2, s[0:1]
	v_mul_f32_e32 v1, 0x4b800000, v3
	v_cndmask_b32_e32 v1, v3, v1, vcc
	v_rsq_f32_e32 v1, v1
	s_nop 0
	v_mul_f32_e32 v2, 0x45800000, v1
	v_cndmask_b32_e32 v147, v1, v2, vcc
	v_mov_b32_e32 v2, v184
	v_mov_b32_e32 v3, v185
	s_nop 0
	v_pk_fma_f32 v[2:3], v[2:3], s[4:5], v[4:5] op_sel_hi:[1,0,0]
	s_nop 0
	v_mul_f32_e32 v1, 0x4b800000, v2
	v_cmp_gt_f32_e64 s[0:1], s72, v2
	v_cmp_gt_f32_e32 vcc, s72, v3
	s_nop 0
	v_cndmask_b32_e64 v1, v2, v1, s[0:1]
	v_rsq_f32_e32 v1, v1
	s_nop 0
	v_mul_f32_e32 v2, 0x45800000, v1
	v_cndmask_b32_e64 v69, v1, v2, s[0:1]
	v_mul_f32_e32 v1, 0x4b800000, v3
	v_cndmask_b32_e32 v1, v3, v1, vcc
	v_rsq_f32_e32 v1, v1
	s_nop 0
	v_mul_f32_e32 v2, 0x45800000, v1
	v_cndmask_b32_e32 v148, v1, v2, vcc
	v_mov_b32_e32 v2, v186
	v_mov_b32_e32 v3, v187
	s_nop 0
	v_pk_fma_f32 v[2:3], v[2:3], s[4:5], v[4:5] op_sel_hi:[1,0,0]
	s_nop 0
	v_mul_f32_e32 v1, 0x4b800000, v2
	v_cmp_gt_f32_e64 s[0:1], s72, v2
	v_cmp_gt_f32_e32 vcc, s72, v3
	s_nop 0
	v_cndmask_b32_e64 v1, v2, v1, s[0:1]
	v_rsq_f32_e32 v1, v1
	s_nop 0
	v_mul_f32_e32 v2, 0x45800000, v1
	v_cndmask_b32_e64 v70, v1, v2, s[0:1]
	v_mul_f32_e32 v1, 0x4b800000, v3
	v_cndmask_b32_e32 v1, v3, v1, vcc
	v_rsq_f32_e32 v1, v1
	s_nop 0
	v_mul_f32_e32 v2, 0x45800000, v1
	v_cndmask_b32_e32 v149, v1, v2, vcc
	v_mov_b32_e32 v2, v188
	v_mov_b32_e32 v3, v189
	s_nop 0
	v_pk_fma_f32 v[2:3], v[2:3], s[4:5], v[4:5] op_sel_hi:[1,0,0]
	s_nop 0
	v_mul_f32_e32 v1, 0x4b800000, v2
	v_cmp_gt_f32_e64 s[0:1], s72, v2
	v_cmp_gt_f32_e32 vcc, s72, v3
	v_lshlrev_b32_e32 v6, 4, v71
	v_cndmask_b32_e64 v1, v2, v1, s[0:1]
	v_rsq_f32_e32 v1, v1
	v_and_b32_e32 v6, 0x70, v6
	v_mul_f32_e32 v2, 0x45800000, v1
	v_cndmask_b32_e64 v1, v1, v2, s[0:1]
	v_mul_f32_e32 v2, 0x4b800000, v3
	v_cndmask_b32_e32 v2, v3, v2, vcc
	v_rsq_f32_e32 v2, v2
	s_lshl_b64 s[0:1], s[54:55], 14
	s_add_u32 s4, s76, s0
	s_addc_u32 s5, s77, s1
	v_mul_f32_e32 v3, 0x45800000, v2
	v_cndmask_b32_e32 v150, v2, v3, vcc
	v_ashrrev_i32_e32 v2, 3, v71
	v_ashrrev_i32_e32 v3, 31, v2
	s_lshl_b32 s0, s13, 19
	v_lshlrev_b64 v[4:5], 7, v[2:3]
	s_add_u32 s0, s9, s0
	v_lshl_add_u64 v[4:5], s[4:5], 0, v[4:5]
	s_addc_u32 s1, s10, 0
	v_lshl_add_u64 v[142:143], v[4:5], 0, v[6:7]
	v_lshlrev_b64 v[4:5], 12, v[2:3]
	v_lshl_add_u64 v[4:5], s[0:1], 0, v[4:5]
	v_lshl_add_u64 v[144:145], v[4:5], 0, v[6:7]
	v_add_co_u32_e32 v4, vcc, s71, v142
	global_load_dwordx4 v[16:19], v[142:143], off
	global_load_dwordx4 v[32:35], v[144:145], off
	v_addc_co_u32_e32 v5, vcc, 0, v143, vcc
	v_add_co_u32_e32 v20, vcc, s69, v144
	global_load_dwordx4 v[44:47], v[4:5], off offset:-4096
	s_nop 0
	v_addc_co_u32_e32 v21, vcc, 0, v145, vcc
	global_load_dwordx4 v[48:51], v[20:21], off
	global_load_dwordx4 v[52:55], v[4:5], off
	v_add_co_u32_e32 v28, vcc, s81, v144
	s_mov_b32 s0, 0x811000
	s_nop 0
	v_addc_co_u32_e32 v29, vcc, 0, v145, vcc
	v_add_co_u32_e32 v4, vcc, s28, v142
	global_load_dwordx4 v[56:59], v[28:29], off
	s_nop 0
	v_addc_co_u32_e32 v5, vcc, 0, v143, vcc
	v_add_co_u32_e32 v40, vcc, s60, v144
	global_load_dwordx4 v[60:63], v[4:5], off
	s_nop 0
	v_addc_co_u32_e32 v41, vcc, 0, v145, vcc
	global_load_dwordx4 v[64:67], v[40:41], off
	v_add_co_u32_e32 v12, vcc, s0, v142
	v_lshlrev_b32_e32 v3, 7, v2
	v_lshrrev_b32_e32 v2, 1, v2
	v_addc_co_u32_e32 v13, vcc, 0, v143, vcc
	s_mov_b32 s0, 0x813000
	v_xor_b32_e32 v2, v2, v71
	v_add_co_u32_e32 v36, vcc, s0, v142
	v_lshlrev_b32_e32 v2, 4, v2
	s_nop 0
	v_addc_co_u32_e32 v37, vcc, 0, v143, vcc
	v_and_or_b32 v151, v2, s91, v3
	global_load_dwordx4 v[4:7], v[12:13], off offset:-4096
	global_load_dwordx4 v[8:11], v[144:145], off offset:128
	s_nop 0
	global_load_dwordx4 v[12:15], v[12:13], off
	s_nop 0
	global_load_dwordx4 v[24:27], v[20:21], off offset:128
	s_nop 0
	global_load_dwordx4 v[20:23], v[36:37], off offset:-4096
	s_nop 0
	global_load_dwordx4 v[28:31], v[28:29], off offset:128
	s_nop 0
	global_load_dwordx4 v[36:39], v[36:37], off
	s_nop 0
	global_load_dwordx4 v[40:43], v[40:41], off offset:128
	s_barrier
; DI void gemm_mainloop(int wv, const u16* __restrict__ A, long lda, long a_kstep, const u16* __restrict__ Bt, long ldb, int K,
;                       char* smc, f32x4 (&acc)[4][4], const bool seg = false, const float* sc0 = nullptr, const float* sc1 = nullptr) {
;     ...
;   __syncthreads();
; #pragma unroll
;   for (int i = 0; i < 4; ++i) {
;     *(u32x4*)(As + swz(lr + 32 * i, lc)) = ra[i];
;     *(u32x4*)(Bs + swz(lr + 32 * i, lc)) = rb[i];
;   }
;   __syncthreads();
;   const int fr = lane & 15, fq = lane >> 4;
;     ...
;   for (int kt = 0; kt < nk; kt += 2) {
;     if (seg && (kt == 12 || kt == 18 || kt == 24)) {
; #pragma unroll
;       for (int i = 0; i < 4; ++i) {
;         const float f = kt == 12 ? 1.f / sc0[i] : (kt == 18 ? sc0[i] / sc1[i] : sc1[i]);
; #pragma unroll
;         for (int j = 0; j < 4; ++j)
; #pragma unroll
;           for (int e = 0; e < 4; ++e) acc[i][j][e] *= f;
;       }
	v_lshrrev_b32_e32 v2, 4, v71
	v_bfe_u32 v3, v71, 4, 2
	s_waitcnt vmcnt(15)
	ds_write_b128 v151, v[16:19]
	s_waitcnt vmcnt(14)
	ds_write_b128 v151, v[32:35] offset:32768
	s_waitcnt vmcnt(13)
	ds_write_b128 v151, v[44:47] offset:4096
	s_waitcnt vmcnt(12)
	ds_write_b128 v151, v[48:51] offset:36864
	s_waitcnt vmcnt(11)
	ds_write_b128 v151, v[52:55] offset:8192
	s_waitcnt vmcnt(10)
	ds_write_b128 v151, v[56:59] offset:40960
	s_waitcnt vmcnt(9)
	ds_write_b128 v151, v[60:63] offset:12288
	s_waitcnt vmcnt(8)
	ds_write_b128 v151, v[64:67] offset:45056
	v_and_b32_e32 v16, 15, v71
	v_lshrrev_b32_e32 v17, 1, v71
	v_and_or_b32 v16, v17, s18, v16
	v_bfe_u32 v17, v71, 1, 3
	v_bitop3_b32 v2, v2, v17, 3 bitop3:0x6c
	v_lshlrev_b32_e32 v152, 4, v2
	v_lshlrev_b32_e32 v2, 7, v71
	v_and_b32_e32 v154, 0x2780, v2
	v_bitop3_b32 v2, v3, v17, 4 bitop3:0x36
	v_lshlrev_b32_e32 v155, 4, v2
	v_div_scale_f32 v2, s[0:1], v147, v147, v68
	v_rcp_f32_e32 v3, v2
	v_lshlrev_b32_e32 v153, 7, v16
	s_waitcnt lgkmcnt(0)
	s_barrier
	v_fma_f32 v16, -v2, v3, 1.0
	v_fmac_f32_e32 v3, v16, v3
	v_div_scale_f32 v16, vcc, v68, v147, v68
	v_mul_f32_e32 v17, v16, v3
	v_fma_f32 v18, -v2, v17, v16
	v_fmac_f32_e32 v17, v18, v3
	v_fma_f32 v2, -v2, v17, v16
	v_div_fmas_f32 v2, v2, v3, v17
	v_div_fixup_f32 v156, v2, v147, v68
	v_div_scale_f32 v2, s[0:1], v68, v68, 1.0
	v_rcp_f32_e32 v3, v2
	s_nop 0
	v_fma_f32 v16, -v2, v3, 1.0
	v_fmac_f32_e32 v3, v16, v3
	v_div_scale_f32 v16, vcc, 1.0, v68, 1.0
	v_mul_f32_e32 v17, v16, v3
	v_fma_f32 v18, -v2, v17, v16
	v_fmac_f32_e32 v17, v18, v3
	v_fma_f32 v2, -v2, v17, v16
	v_div_fmas_f32 v2, v2, v3, v17
	v_div_fixup_f32 v157, v2, v68, 1.0
	v_div_scale_f32 v2, s[0:1], v148, v148, v69
	v_rcp_f32_e32 v3, v2
	s_nop 0
	v_fma_f32 v16, -v2, v3, 1.0
	v_fmac_f32_e32 v3, v16, v3
	v_div_scale_f32 v16, vcc, v69, v148, v69
	v_mul_f32_e32 v17, v16, v3
	v_fma_f32 v18, -v2, v17, v16
	v_fmac_f32_e32 v17, v18, v3
	v_fma_f32 v2, -v2, v17, v16
	v_div_fmas_f32 v2, v2, v3, v17
	v_div_fixup_f32 v158, v2, v148, v69
	v_div_scale_f32 v2, s[0:1], v69, v69, 1.0
	v_rcp_f32_e32 v3, v2
	s_nop 0
	v_fma_f32 v16, -v2, v3, 1.0
	v_fmac_f32_e32 v3, v16, v3
	v_div_scale_f32 v16, vcc, 1.0, v69, 1.0
	v_mul_f32_e32 v17, v16, v3
	v_fma_f32 v18, -v2, v17, v16
	v_fmac_f32_e32 v17, v18, v3
	v_fma_f32 v2, -v2, v17, v16
	v_div_fmas_f32 v2, v2, v3, v17
	v_div_fixup_f32 v159, v2, v69, 1.0
	v_div_scale_f32 v2, s[0:1], v149, v149, v70
	v_rcp_f32_e32 v3, v2
	s_nop 0
	v_fma_f32 v16, -v2, v3, 1.0
	v_fmac_f32_e32 v3, v16, v3
	v_div_scale_f32 v16, vcc, v70, v149, v70
	v_mul_f32_e32 v17, v16, v3
	v_fma_f32 v18, -v2, v17, v16
	v_fmac_f32_e32 v17, v18, v3
	v_fma_f32 v2, -v2, v17, v16
	v_div_fmas_f32 v2, v2, v3, v17
	v_div_fixup_f32 v160, v2, v149, v70
	v_div_scale_f32 v2, s[0:1], v70, v70, 1.0
	v_rcp_f32_e32 v3, v2
	s_nop 0
	v_fma_f32 v16, -v2, v3, 1.0
	v_fmac_f32_e32 v3, v16, v3
	v_div_scale_f32 v16, vcc, 1.0, v70, 1.0
	v_mul_f32_e32 v17, v16, v3
	v_fma_f32 v18, -v2, v17, v16
	v_fmac_f32_e32 v17, v18, v3
	v_fma_f32 v2, -v2, v17, v16
	v_div_fmas_f32 v2, v2, v3, v17
	v_div_fixup_f32 v161, v2, v70, 1.0
	v_div_scale_f32 v2, s[0:1], v150, v150, v1
	v_rcp_f32_e32 v3, v2
	s_nop 0
	v_fma_f32 v16, -v2, v3, 1.0
	v_fmac_f32_e32 v3, v16, v3
	v_div_scale_f32 v16, vcc, v1, v150, v1
	v_mul_f32_e32 v17, v16, v3
	v_fma_f32 v18, -v2, v17, v16
	v_fmac_f32_e32 v17, v18, v3
	v_fma_f32 v2, -v2, v17, v16
	v_div_fmas_f32 v2, v2, v3, v17
	v_div_fixup_f32 v162, v2, v150, v1
	v_div_scale_f32 v2, s[0:1], v1, v1, 1.0
	v_rcp_f32_e32 v3, v2
	s_nop 0
	v_fma_f32 v16, -v2, v3, 1.0
	v_fmac_f32_e32 v3, v16, v3
	v_div_scale_f32 v16, vcc, 1.0, v1, 1.0
	v_mul_f32_e32 v17, v16, v3
	v_fma_f32 v18, -v2, v17, v16
	v_fmac_f32_e32 v17, v18, v3
	v_fma_f32 v2, -v2, v17, v16
	v_div_fmas_f32 v2, v2, v3, v17
	v_div_fixup_f32 v163, v2, v1, 1.0
	v_mov_b32_e32 v2, v0
	v_mov_b32_e32 v3, v0
	v_mov_b32_e32 v1, v0
	v_mov_b64_e32 v[18:19], v[2:3]
	v_mov_b64_e32 v[34:35], v[2:3]
	v_mov_b64_e32 v[46:47], v[2:3]
	v_mov_b64_e32 v[50:51], v[2:3]
	v_mov_b64_e32 v[54:55], v[2:3]
	v_mov_b64_e32 v[58:59], v[2:3]
	v_mov_b64_e32 v[62:63], v[2:3]
	v_mov_b64_e32 v[66:67], v[2:3]
	v_mov_b64_e32 v[70:71], v[2:3]
	v_mov_b64_e32 v[74:75], v[2:3]
	v_mov_b64_e32 v[78:79], v[2:3]
	v_mov_b64_e32 v[82:83], v[2:3]
	v_mov_b64_e32 v[86:87], v[2:3]
	v_mov_b64_e32 v[90:91], v[2:3]
	v_mov_b64_e32 v[94:95], v[2:3]
	v_mov_b64_e32 v[98:99], v[2:3]
	v_mov_b64_e32 v[16:17], v[0:1]
	v_mov_b64_e32 v[32:33], v[0:1]
	v_mov_b64_e32 v[44:45], v[0:1]
	v_mov_b64_e32 v[48:49], v[0:1]
	v_mov_b64_e32 v[52:53], v[0:1]
	v_mov_b64_e32 v[56:57], v[0:1]
	v_mov_b64_e32 v[60:61], v[0:1]
	v_mov_b64_e32 v[64:65], v[0:1]
	v_mov_b64_e32 v[68:69], v[0:1]
	v_mov_b64_e32 v[72:73], v[0:1]
	v_mov_b64_e32 v[76:77], v[0:1]
	v_mov_b64_e32 v[80:81], v[0:1]
	v_mov_b64_e32 v[84:85], v[0:1]
	v_mov_b64_e32 v[88:89], v[0:1]
	v_mov_b64_e32 v[92:93], v[0:1]
	v_mov_b64_e32 v[96:97], v[0:1]
	s_cmp_lt_i32 s14, 18
	s_cbranch_scc1 .LBB0_863

; DI const float* xrow(const Params& p, int layer, long row) {
;   if (layer == 0) return row < MP ? p.in[0] + row * DM : p.in[1] + (row - MP) * DM;
;   return p.out + row * DM;
; }
; DI void phase_outproj(int wv, const Params& p, int layer, char* smc) {
;     ...
; #pragma unroll
;     for (int i = 0; i < 4; ++i) {
;       const long row = (long)tm * 128 + wm * 64 + i * 16 + fr;
;       const float* xi = xrow(p, layer, row);
;       float* yo = p.out + row * DM;
; #pragma unroll
;       for (int n = 0; n < 4; ++n) {
;         const int col = tn * 128 + wn * 64 + n * 16 + 4 * fq;
;         const f32x4 x4 = __builtin_nontemporal_load((const f32x4*)(xi + col));
;         __builtin_nontemporal_store(x4 + acc[i][n], (f32x4*)(yo + col));
;       }
;     }
.LBB0_898:
	s_waitcnt vmcnt(0)
	v_lshl_or_b32 v1, s13, 7, v146
	v_lshlrev_b32_e32 v2, 2, v1
	v_mov_b32_e32 v3, v0
	s_and_b64 vcc, exec, s[2:3]
	s_cbranch_vccz .Lop_l0
	s_mov_b64 s[4:5], s[56:57]
	s_mov_b64 s[6:7], s[56:57]
	s_branch .Lop_x
.Lop_l0:
	s_mov_b64 s[4:5], s[36:37]
	s_add_u32 s6, s38, 0xf0000000
	s_addc_u32 s7, s39, -1
.Lop_x:
	v_mov_b32_e32 v6, s4
	v_mov_b32_e32 v7, s5
	v_mov_b32_e32 v8, s6
	v_mov_b32_e32 v9, s7
	v_cmp_lt_i64_e32 vcc, s[20:21], v[140:141]
	v_lshlrev_b64 v[4:5], 12, v[140:141]
	v_lshl_add_u64 v[12:13], s[56:57], 0, v[4:5]
	v_cndmask_b32_e32 v10, v6, v8, vcc
	v_cndmask_b32_e32 v11, v7, v9, vcc
	v_lshl_add_u64 v[100:101], v[12:13], 0, v[2:3]
	v_lshl_add_u64 v[10:11], v[10:11], 0, v[4:5]
	v_lshl_add_u64 v[10:11], v[10:11], 0, v[2:3]
	global_load_dwordx4 v[184:187], v[10:11], off nt
	global_load_dwordx4 v[188:191], v[10:11], off offset:64 nt
	global_load_dwordx4 v[192:195], v[10:11], off offset:128 nt
	global_load_dwordx4 v[196:199], v[10:11], off offset:192 nt
	v_cmp_lt_i64_e32 vcc, s[20:21], v[138:139]
	v_lshlrev_b64 v[4:5], 12, v[138:139]
	v_lshl_add_u64 v[12:13], s[56:57], 0, v[4:5]
	v_cndmask_b32_e32 v10, v6, v8, vcc
	v_cndmask_b32_e32 v11, v7, v9, vcc
	v_lshl_add_u64 v[102:103], v[12:13], 0, v[2:3]
	v_lshl_add_u64 v[10:11], v[10:11], 0, v[4:5]
	v_lshl_add_u64 v[10:11], v[10:11], 0, v[2:3]
	global_load_dwordx4 v[200:203], v[10:11], off nt
	global_load_dwordx4 v[204:207], v[10:11], off offset:64 nt
	global_load_dwordx4 v[220:223], v[10:11], off offset:128 nt
	global_load_dwordx4 v[224:227], v[10:11], off offset:192 nt
	v_cmp_lt_i64_e32 vcc, s[20:21], v[136:137]
	v_lshlrev_b64 v[4:5], 12, v[136:137]
	v_lshl_add_u64 v[12:13], s[56:57], 0, v[4:5]
	v_cndmask_b32_e32 v10, v6, v8, vcc
	v_cndmask_b32_e32 v11, v7, v9, vcc
	v_lshl_add_u64 v[104:105], v[12:13], 0, v[2:3]
	v_lshl_add_u64 v[10:11], v[10:11], 0, v[4:5]
	v_lshl_add_u64 v[10:11], v[10:11], 0, v[2:3]
	global_load_dwordx4 v[228:231], v[10:11], off nt
	global_load_dwordx4 v[232:235], v[10:11], off offset:64 nt
	global_load_dwordx4 v[236:239], v[10:11], off offset:128 nt
	global_load_dwordx4 v[240:243], v[10:11], off offset:192 nt
	v_cmp_lt_i64_e32 vcc, s[20:21], v[134:135]
	v_lshlrev_b64 v[4:5], 12, v[134:135]
	v_lshl_add_u64 v[12:13], s[56:57], 0, v[4:5]
	v_cndmask_b32_e32 v10, v6, v8, vcc
	v_cndmask_b32_e32 v11, v7, v9, vcc
	v_lshl_add_u64 v[106:107], v[12:13], 0, v[2:3]
	v_lshl_add_u64 v[10:11], v[10:11], 0, v[4:5]
	v_lshl_add_u64 v[10:11], v[10:11], 0, v[2:3]
	global_load_dwordx4 v[244:247], v[10:11], off nt
	global_load_dwordx4 v[248:251], v[10:11], off offset:64 nt
	global_load_dwordx4 v[108:111], v[10:11], off offset:128 nt
	global_load_dwordx4 v[112:115], v[10:11], off offset:192 nt
	s_waitcnt vmcnt(0)
	v_pk_add_f32 v[184:185], v[96:97], v[184:185]
	v_pk_add_f32 v[186:187], v[98:99], v[186:187]
	global_store_dwordx4 v[100:101], v[184:187], off nt
	v_pk_add_f32 v[188:189], v[92:93], v[188:189]
	v_pk_add_f32 v[190:191], v[94:95], v[190:191]
	global_store_dwordx4 v[100:101], v[188:191], off offset:64 nt
	v_pk_add_f32 v[192:193], v[88:89], v[192:193]
	v_pk_add_f32 v[194:195], v[90:91], v[194:195]
	global_store_dwordx4 v[100:101], v[192:195], off offset:128 nt
	v_pk_add_f32 v[196:197], v[84:85], v[196:197]
	v_pk_add_f32 v[198:199], v[86:87], v[198:199]
	global_store_dwordx4 v[100:101], v[196:199], off offset:192 nt
	v_pk_add_f32 v[200:201], v[80:81], v[200:201]
	v_pk_add_f32 v[202:203], v[82:83], v[202:203]
	global_store_dwordx4 v[102:103], v[200:203], off nt
	v_pk_add_f32 v[204:205], v[76:77], v[204:205]
	v_pk_add_f32 v[206:207], v[78:79], v[206:207]
	global_store_dwordx4 v[102:103], v[204:207], off offset:64 nt
	v_pk_add_f32 v[220:221], v[72:73], v[220:221]
	v_pk_add_f32 v[222:223], v[74:75], v[222:223]
	global_store_dwordx4 v[102:103], v[220:223], off offset:128 nt
	v_pk_add_f32 v[224:225], v[68:69], v[224:225]
	v_pk_add_f32 v[226:227], v[70:71], v[226:227]
	global_store_dwordx4 v[102:103], v[224:227], off offset:192 nt
	v_pk_add_f32 v[228:229], v[64:65], v[228:229]
	v_pk_add_f32 v[230:231], v[66:67], v[230:231]
	global_store_dwordx4 v[104:105], v[228:231], off nt
	v_pk_add_f32 v[232:233], v[60:61], v[232:233]
	v_pk_add_f32 v[234:235], v[62:63], v[234:235]
	global_store_dwordx4 v[104:105], v[232:235], off offset:64 nt
	v_pk_add_f32 v[236:237], v[56:57], v[236:237]
	v_pk_add_f32 v[238:239], v[58:59], v[238:239]
	global_store_dwordx4 v[104:105], v[236:239], off offset:128 nt
	v_pk_add_f32 v[240:241], v[52:53], v[240:241]
	v_pk_add_f32 v[242:243], v[54:55], v[242:243]
	global_store_dwordx4 v[104:105], v[240:243], off offset:192 nt
	v_pk_add_f32 v[244:245], v[48:49], v[244:245]
	v_pk_add_f32 v[246:247], v[50:51], v[246:247]
	global_store_dwordx4 v[106:107], v[244:247], off nt
	v_pk_add_f32 v[248:249], v[44:45], v[248:249]
	v_pk_add_f32 v[250:251], v[46:47], v[250:251]
	global_store_dwordx4 v[106:107], v[248:251], off offset:64 nt
	v_pk_add_f32 v[108:109], v[32:33], v[108:109]
	v_pk_add_f32 v[110:111], v[34:35], v[110:111]
	global_store_dwordx4 v[106:107], v[108:111], off offset:128 nt
	v_pk_add_f32 v[112:113], v[16:17], v[112:113]
	v_pk_add_f32 v[114:115], v[18:19], v[114:115]
	global_store_dwordx4 v[106:107], v[112:115], off offset:192 nt
	s_branch .Lop_next
